# saddr LDS-DMA + unscaled f8f6f4 MFMA (unit scales dropped) in FFN2 GEMMs
# speedup vs baseline: 1.0071x; 1.0026x over previous
.LBB0_2480:
	ds_read_b128 v[18:21], v182
	ds_read_b128 v[22:25], v182 offset:1024
	ds_read_b128 v[26:29], v182 offset:2048
	ds_read_b128 v[30:33], v182 offset:3072
	ds_read_b128 v[2:5], v183
	ds_read_b128 v[6:9], v183 offset:1024
	ds_read_b128 v[10:13], v183 offset:2048
	ds_read_b128 v[14:17], v183 offset:3072
	s_add_u32 s26, s24, 0xfc000
	s_addc_u32 s27, s25, 0
	s_cmp_eq_u32 s48, 28
	s_cselect_b32 s30, s17, s26
	s_cselect_b32 s31, s5, s27
	s_cselect_b32 s28, s23, s46
	s_cselect_b32 s29, s15, s47
	s_add_u32 s26, s30, 0x100000
	s_addc_u32 s27, s31, 0
	s_add_i32 m0, s34, 0xc000
	ds_read_b128 v[186:189], v184
	ds_read_b128 v[190:193], v184 offset:1024
	ds_read_b128 v[220:223], v184 offset:2048
	ds_read_b128 v[224:227], v184 offset:3072
	ds_read_b128 v[228:231], v184 offset:4096
	ds_read_b128 v[232:235], v184 offset:5120
	ds_read_b128 v[236:239], v184 offset:6144
	ds_read_b128 v[240:243], v184 offset:7168
	global_load_lds_dwordx4 v172, s[24:25]
	s_add_i32 m0, s34, 0xe000
	s_nop 0
	global_load_lds_dwordx4 v174, s[24:25]
	s_waitcnt vmcnt(8)
	s_waitcnt lgkmcnt(0)
	s_barrier
	s_setprio 1
	s_waitcnt lgkmcnt(0)
	v_mfma_f32_16x16x128_f8f6f4 v[158:161], v[18:25], v[186:193], v[158:161]
	v_mfma_f32_16x16x128_f8f6f4 v[154:157], v[26:33], v[186:193], v[154:157]
	v_mfma_f32_16x16x128_f8f6f4 v[142:145], v[18:25], v[220:227], v[142:145]
	v_mfma_f32_16x16x128_f8f6f4 v[138:141], v[26:33], v[220:227], v[138:141]
	v_mfma_f32_16x16x128_f8f6f4 v[126:129], v[18:25], v[228:235], v[126:129]
	v_mfma_f32_16x16x128_f8f6f4 v[122:125], v[26:33], v[228:235], v[122:125]
	v_mfma_f32_16x16x128_f8f6f4 v[110:113], v[18:25], v[236:243], v[110:113]
	v_mfma_f32_16x16x128_f8f6f4 v[106:109], v[26:33], v[236:243], v[106:109]
	s_setprio 0
	s_setprio 1
	v_mfma_f32_16x16x128_f8f6f4 v[150:153], v[2:9], v[186:193], v[150:153]
	v_mfma_f32_16x16x128_f8f6f4 v[146:149], v[10:17], v[186:193], v[146:149]
	v_mfma_f32_16x16x128_f8f6f4 v[134:137], v[2:9], v[220:227], v[134:137]
	v_mfma_f32_16x16x128_f8f6f4 v[130:133], v[10:17], v[220:227], v[130:133]
	v_mfma_f32_16x16x128_f8f6f4 v[118:121], v[2:9], v[228:235], v[118:121]
	v_mfma_f32_16x16x128_f8f6f4 v[114:117], v[10:17], v[228:235], v[114:117]
	v_mfma_f32_16x16x128_f8f6f4 v[102:105], v[2:9], v[236:243], v[102:105]
	v_mfma_f32_16x16x128_f8f6f4 v[98:101], v[10:17], v[236:243], v[98:101]
	s_setprio 0
	s_barrier
	s_add_i32 s49, s42, s0
	s_mov_b32 m0, s49
	ds_read_b128 v[186:189], v184 offset:16384
	ds_read_b128 v[190:193], v184 offset:17408
	ds_read_b128 v[220:223], v184 offset:18432
	ds_read_b128 v[224:227], v184 offset:19456
	ds_read_b128 v[228:231], v184 offset:20480
	ds_read_b128 v[232:235], v184 offset:21504
	ds_read_b128 v[236:239], v184 offset:22528
	ds_read_b128 v[240:243], v184 offset:23552
	global_load_lds_dwordx4 v166, s[28:29]
	s_add_i32 m0, s49, 0x2000
	s_add_u32 s50, s28, 0x4000
	s_addc_u32 s51, s29, 0
	s_add_i32 s49, s43, s0
	global_load_lds_dwordx4 v162, s[28:29]
	s_mov_b32 m0, s49
	s_nop 0
	global_load_lds_dwordx4 v166, s[50:51]
	s_add_i32 m0, s49, 0x2000
	s_nop 0
	global_load_lds_dwordx4 v162, s[50:51]
	s_mov_b32 m0, s34
	s_nop 0
	global_load_lds_dwordx4 v168, s[30:31]
	s_mov_b32 m0, s35
	s_nop 0
	global_load_lds_dwordx4 v164, s[30:31]
	s_waitcnt vmcnt(8)
	s_waitcnt lgkmcnt(0)
	s_barrier
	s_setprio 1
	s_waitcnt lgkmcnt(0)
	v_mfma_f32_16x16x128_f8f6f4 v[94:97], v[18:25], v[186:193], v[94:97]
	v_mfma_f32_16x16x128_f8f6f4 v[90:93], v[26:33], v[186:193], v[90:93]
	v_mfma_f32_16x16x128_f8f6f4 v[78:81], v[18:25], v[220:227], v[78:81]
	v_mfma_f32_16x16x128_f8f6f4 v[74:77], v[26:33], v[220:227], v[74:77]
	v_mfma_f32_16x16x128_f8f6f4 v[62:65], v[18:25], v[228:235], v[62:65]
	v_mfma_f32_16x16x128_f8f6f4 v[58:61], v[26:33], v[228:235], v[58:61]
	v_mfma_f32_16x16x128_f8f6f4 v[46:49], v[18:25], v[236:243], v[46:49]
	v_mfma_f32_16x16x128_f8f6f4 v[42:45], v[26:33], v[236:243], v[42:45]
	s_setprio 0
	s_setprio 1
	v_mfma_f32_16x16x128_f8f6f4 v[86:89], v[2:9], v[186:193], v[86:89]
	v_mfma_f32_16x16x128_f8f6f4 v[82:85], v[10:17], v[186:193], v[82:85]
	v_mfma_f32_16x16x128_f8f6f4 v[70:73], v[2:9], v[220:227], v[70:73]
	v_mfma_f32_16x16x128_f8f6f4 v[66:69], v[10:17], v[220:227], v[66:69]
	v_mfma_f32_16x16x128_f8f6f4 v[54:57], v[2:9], v[228:235], v[54:57]
	v_mfma_f32_16x16x128_f8f6f4 v[50:53], v[10:17], v[228:235], v[50:53]
	v_mfma_f32_16x16x128_f8f6f4 v[38:41], v[2:9], v[236:243], v[38:41]
	v_mfma_f32_16x16x128_f8f6f4 v[34:37], v[10:17], v[236:243], v[34:37]
	s_setprio 0
	s_barrier
	s_add_i32 s49, 0, 0x18000
	s_add_i32 s50, 0, 0x1c000
	v_add_u32_e32 v14, s49, v181
	v_add_u32_e32 v30, s50, v181
	ds_read_b128 v[2:5], v14
	ds_read_b128 v[6:9], v14 offset:1024
	ds_read_b128 v[10:13], v14 offset:2048
	ds_read_b128 v[14:17], v14 offset:3072
	ds_read_b128 v[18:21], v30
	ds_read_b128 v[22:25], v30 offset:1024
	ds_read_b128 v[26:29], v30 offset:2048
	ds_read_b128 v[30:33], v30 offset:3072
	s_add_u32 s30, s30, 0x4000
	s_addc_u32 s31, s31, 0
	s_mov_b32 m0, s36
	ds_read_b128 v[186:189], v184 offset:32768
	ds_read_b128 v[190:193], v184 offset:33792
	ds_read_b128 v[220:223], v184 offset:34816
	ds_read_b128 v[224:227], v184 offset:35840
	ds_read_b128 v[228:231], v184 offset:36864
	ds_read_b128 v[232:235], v184 offset:37888
	ds_read_b128 v[236:239], v184 offset:38912
	ds_read_b128 v[240:243], v184 offset:39936
	global_load_lds_dwordx4 v168, s[30:31]
	s_mov_b32 m0, s37
	s_nop 0
	global_load_lds_dwordx4 v164, s[30:31]
	s_waitcnt vmcnt(8)
	s_waitcnt lgkmcnt(0)
	s_barrier
	s_setprio 1
	s_waitcnt lgkmcnt(0)
	v_mfma_f32_16x16x128_f8f6f4 v[158:161], v[2:9], v[186:193], v[158:161]
	v_mfma_f32_16x16x128_f8f6f4 v[154:157], v[10:17], v[186:193], v[154:157]
	v_mfma_f32_16x16x128_f8f6f4 v[142:145], v[2:9], v[220:227], v[142:145]
	v_mfma_f32_16x16x128_f8f6f4 v[138:141], v[10:17], v[220:227], v[138:141]
	v_mfma_f32_16x16x128_f8f6f4 v[126:129], v[2:9], v[228:235], v[126:129]
	v_mfma_f32_16x16x128_f8f6f4 v[122:125], v[10:17], v[228:235], v[122:125]
	v_mfma_f32_16x16x128_f8f6f4 v[110:113], v[2:9], v[236:243], v[110:113]
	v_mfma_f32_16x16x128_f8f6f4 v[106:109], v[10:17], v[236:243], v[106:109]
	s_setprio 0
	s_setprio 1
	v_mfma_f32_16x16x128_f8f6f4 v[150:153], v[18:25], v[186:193], v[150:153]
	v_mfma_f32_16x16x128_f8f6f4 v[146:149], v[26:33], v[186:193], v[146:149]
	v_mfma_f32_16x16x128_f8f6f4 v[134:137], v[18:25], v[220:227], v[134:137]
	v_mfma_f32_16x16x128_f8f6f4 v[130:133], v[26:33], v[220:227], v[130:133]
	v_mfma_f32_16x16x128_f8f6f4 v[118:121], v[18:25], v[228:235], v[118:121]
	v_mfma_f32_16x16x128_f8f6f4 v[114:117], v[26:33], v[228:235], v[114:117]
	v_mfma_f32_16x16x128_f8f6f4 v[102:105], v[18:25], v[236:243], v[102:105]
	v_mfma_f32_16x16x128_f8f6f4 v[98:101], v[26:33], v[236:243], v[98:101]
	s_setprio 0
	s_barrier
	s_add_u32 s30, s28, 0x380000
	s_addc_u32 s31, s29, 0
	s_add_i32 s49, s49, s0
	s_mov_b32 m0, s49
	ds_read_b128 v[186:189], v184 offset:49152
	ds_read_b128 v[190:193], v184 offset:50176
	ds_read_b128 v[220:223], v184 offset:51200
	ds_read_b128 v[224:227], v184 offset:52224
	ds_read_b128 v[228:231], v184 offset:53248
	ds_read_b128 v[232:235], v184 offset:54272
	ds_read_b128 v[236:239], v184 offset:55296
	ds_read_b128 v[240:243], v184 offset:56320
	global_load_lds_dwordx4 v166, s[30:31]
	s_add_i32 m0, s49, 0x2000
	s_add_u32 s28, s28, 0x384000
	s_addc_u32 s29, s29, 0
	global_load_lds_dwordx4 v162, s[30:31]
	s_add_i32 s30, s50, s0
	s_mov_b32 m0, s30
	s_nop 0
	global_load_lds_dwordx4 v166, s[28:29]
	s_add_i32 m0, s30, 0x2000
	s_nop 0
	global_load_lds_dwordx4 v162, s[28:29]
	s_mov_b32 m0, s40
	s_nop 0
	global_load_lds_dwordx4 v168, s[26:27]
	s_mov_b32 m0, s41
	s_nop 0
	global_load_lds_dwordx4 v164, s[26:27]
	s_waitcnt vmcnt(8)
	s_waitcnt lgkmcnt(0)
	s_barrier
	s_setprio 1
	s_waitcnt lgkmcnt(0)
	v_mfma_f32_16x16x128_f8f6f4 v[94:97], v[2:9], v[186:193], v[94:97]
	v_mfma_f32_16x16x128_f8f6f4 v[90:93], v[10:17], v[186:193], v[90:93]
	v_mfma_f32_16x16x128_f8f6f4 v[78:81], v[2:9], v[220:227], v[78:81]
	v_mfma_f32_16x16x128_f8f6f4 v[74:77], v[10:17], v[220:227], v[74:77]
	v_mfma_f32_16x16x128_f8f6f4 v[62:65], v[2:9], v[228:235], v[62:65]
	v_mfma_f32_16x16x128_f8f6f4 v[58:61], v[10:17], v[228:235], v[58:61]
	v_mfma_f32_16x16x128_f8f6f4 v[46:49], v[2:9], v[236:243], v[46:49]
	v_mfma_f32_16x16x128_f8f6f4 v[42:45], v[10:17], v[236:243], v[42:45]
	s_setprio 0
	s_setprio 1
	v_mfma_f32_16x16x128_f8f6f4 v[86:89], v[18:25], v[186:193], v[86:89]
	v_mfma_f32_16x16x128_f8f6f4 v[82:85], v[26:33], v[186:193], v[82:85]
	v_mfma_f32_16x16x128_f8f6f4 v[70:73], v[18:25], v[220:227], v[70:73]
	v_mfma_f32_16x16x128_f8f6f4 v[66:69], v[26:33], v[220:227], v[66:69]
	v_mfma_f32_16x16x128_f8f6f4 v[54:57], v[18:25], v[228:235], v[54:57]
	v_mfma_f32_16x16x128_f8f6f4 v[50:53], v[26:33], v[228:235], v[50:53]
	v_mfma_f32_16x16x128_f8f6f4 v[38:41], v[18:25], v[236:243], v[38:41]
	v_mfma_f32_16x16x128_f8f6f4 v[34:37], v[26:33], v[236:243], v[34:37]
	s_setprio 0
	s_barrier
	s_add_i32 s48, s48, 2
	s_add_u32 s46, s46, 0x700000
	s_addc_u32 s47, s47, 0
	s_add_u32 s24, s24, 0x200000
	s_addc_u32 s25, s25, 0
	s_cmp_gt_u32 s48, 29
	s_cbranch_scc0 .LBB0_2480
	s_and_b64 vcc, exec, s[8:9]
	s_cbranch_vccz .LBB0_2483
	s_barrier

.LBB0_2714:
	ds_read_b128 v[18:21], v180
	ds_read_b128 v[22:25], v180 offset:1024
	ds_read_b128 v[26:29], v180 offset:2048
	ds_read_b128 v[30:33], v180 offset:3072
	s_waitcnt lgkmcnt(0)
	ds_read_b128 v[2:5], v181
	ds_read_b128 v[6:9], v181 offset:1024
	ds_read_b128 v[10:13], v181 offset:2048
	ds_read_b128 v[14:17], v181 offset:3072
	s_add_u32 s24, s22, 0xfc000
	s_addc_u32 s25, s23, 0
	s_cmpk_eq_i32 s44, 0x6c
	s_cselect_b32 s28, s17, s24
	s_cselect_b32 s29, s5, s25
	s_cselect_b32 s26, s41, s42
	s_cselect_b32 s27, s15, s43
	s_add_u32 s24, s28, 0x100000
	s_addc_u32 s25, s29, 0
	s_add_i32 m0, s1, 0xc000
	ds_read_b128 v[184:187], v182
	ds_read_b128 v[188:191], v182 offset:1024
	ds_read_b128 v[192:195], v182 offset:2048
	ds_read_b128 v[196:199], v182 offset:3072
	ds_read_b128 v[220:223], v182 offset:4096
	ds_read_b128 v[224:227], v182 offset:5120
	ds_read_b128 v[228:231], v182 offset:6144
	ds_read_b128 v[232:235], v182 offset:7168
	global_load_lds_dwordx4 v170, s[22:23]
	s_add_i32 m0, s1, 0xe000
	s_nop 0
	global_load_lds_dwordx4 v172, s[22:23]
	s_waitcnt vmcnt(8)
	s_waitcnt lgkmcnt(0)
	s_barrier
	s_setprio 1
	s_waitcnt lgkmcnt(0)
	v_mfma_f32_16x16x128_f8f6f4 v[158:161], v[18:25], v[184:191], v[158:161]
	v_mfma_f32_16x16x128_f8f6f4 v[154:157], v[26:33], v[184:191], v[154:157]
	v_mfma_f32_16x16x128_f8f6f4 v[142:145], v[18:25], v[192:199], v[142:145]
	v_mfma_f32_16x16x128_f8f6f4 v[138:141], v[26:33], v[192:199], v[138:141]
	v_mfma_f32_16x16x128_f8f6f4 v[126:129], v[18:25], v[220:227], v[126:129]
	v_mfma_f32_16x16x128_f8f6f4 v[122:125], v[26:33], v[220:227], v[122:125]
	v_mfma_f32_16x16x128_f8f6f4 v[110:113], v[18:25], v[228:235], v[110:113]
	v_mfma_f32_16x16x128_f8f6f4 v[106:109], v[26:33], v[228:235], v[106:109]
	s_setprio 0
	s_setprio 1
	v_mfma_f32_16x16x128_f8f6f4 v[150:153], v[2:9], v[184:191], v[150:153]
	v_mfma_f32_16x16x128_f8f6f4 v[146:149], v[10:17], v[184:191], v[146:149]
	v_mfma_f32_16x16x128_f8f6f4 v[134:137], v[2:9], v[192:199], v[134:137]
	v_mfma_f32_16x16x128_f8f6f4 v[130:133], v[10:17], v[192:199], v[130:133]
	v_mfma_f32_16x16x128_f8f6f4 v[118:121], v[2:9], v[220:227], v[118:121]
	v_mfma_f32_16x16x128_f8f6f4 v[114:117], v[10:17], v[220:227], v[114:117]
	v_mfma_f32_16x16x128_f8f6f4 v[102:105], v[2:9], v[228:235], v[102:105]
	v_mfma_f32_16x16x128_f8f6f4 v[98:101], v[10:17], v[228:235], v[98:101]
	s_setprio 0
	s_barrier
	s_add_i32 s45, s38, s0
	s_mov_b32 m0, s45
	ds_read_b128 v[184:187], v182 offset:16384
	ds_read_b128 v[188:191], v182 offset:17408
	ds_read_b128 v[192:195], v182 offset:18432
	ds_read_b128 v[196:199], v182 offset:19456
	ds_read_b128 v[220:223], v182 offset:20480
	ds_read_b128 v[224:227], v182 offset:21504
	ds_read_b128 v[228:231], v182 offset:22528
	ds_read_b128 v[232:235], v182 offset:23552
	global_load_lds_dwordx4 v164, s[26:27]
	s_add_i32 m0, s45, 0x2000
	s_add_u32 s46, s26, 0x4000
	s_addc_u32 s47, s27, 0
	s_add_i32 s45, s39, s0
	global_load_lds_dwordx4 v168, s[26:27]
	s_mov_b32 m0, s45
	s_nop 0
	global_load_lds_dwordx4 v164, s[46:47]
	s_add_i32 m0, s45, 0x2000
	s_nop 0
	global_load_lds_dwordx4 v168, s[46:47]
	s_mov_b32 m0, s1
	s_nop 0
	global_load_lds_dwordx4 v162, s[28:29]
	s_mov_b32 m0, s13
	s_nop 0
	global_load_lds_dwordx4 v166, s[28:29]
	s_waitcnt vmcnt(8)
	s_waitcnt lgkmcnt(0)
	s_barrier
	s_setprio 1
	s_waitcnt lgkmcnt(0)
	v_mfma_f32_16x16x128_f8f6f4 v[94:97], v[18:25], v[184:191], v[94:97]
	v_mfma_f32_16x16x128_f8f6f4 v[90:93], v[26:33], v[184:191], v[90:93]
	v_mfma_f32_16x16x128_f8f6f4 v[78:81], v[18:25], v[192:199], v[78:81]
	v_mfma_f32_16x16x128_f8f6f4 v[74:77], v[26:33], v[192:199], v[74:77]
	v_mfma_f32_16x16x128_f8f6f4 v[62:65], v[18:25], v[220:227], v[62:65]
	v_mfma_f32_16x16x128_f8f6f4 v[58:61], v[26:33], v[220:227], v[58:61]
	v_mfma_f32_16x16x128_f8f6f4 v[46:49], v[18:25], v[228:235], v[46:49]
	v_mfma_f32_16x16x128_f8f6f4 v[42:45], v[26:33], v[228:235], v[42:45]
	s_setprio 0
	s_setprio 1
	v_mfma_f32_16x16x128_f8f6f4 v[86:89], v[2:9], v[184:191], v[86:89]
	v_mfma_f32_16x16x128_f8f6f4 v[82:85], v[10:17], v[184:191], v[82:85]
	v_mfma_f32_16x16x128_f8f6f4 v[70:73], v[2:9], v[192:199], v[70:73]
	v_mfma_f32_16x16x128_f8f6f4 v[66:69], v[10:17], v[192:199], v[66:69]
	v_mfma_f32_16x16x128_f8f6f4 v[54:57], v[2:9], v[220:227], v[54:57]
	v_mfma_f32_16x16x128_f8f6f4 v[50:53], v[10:17], v[220:227], v[50:53]
	v_mfma_f32_16x16x128_f8f6f4 v[38:41], v[2:9], v[228:235], v[38:41]
	v_mfma_f32_16x16x128_f8f6f4 v[34:37], v[10:17], v[228:235], v[34:37]
	s_setprio 0
	s_barrier
	s_add_i32 s45, 0, 0x18000
	s_add_i32 s46, 0, 0x1c000
	v_add_u32_e32 v14, s45, v179
	v_add_u32_e32 v30, s46, v179
	ds_read_b128 v[2:5], v14
	ds_read_b128 v[6:9], v14 offset:1024
	ds_read_b128 v[10:13], v14 offset:2048
	ds_read_b128 v[14:17], v14 offset:3072
	ds_read_b128 v[18:21], v30
	ds_read_b128 v[22:25], v30 offset:1024
	ds_read_b128 v[26:29], v30 offset:2048
	ds_read_b128 v[30:33], v30 offset:3072
	s_add_u32 s28, s28, 0x4000
	s_addc_u32 s29, s29, 0
	s_mov_b32 m0, s30
	ds_read_b128 v[184:187], v182 offset:32768
	ds_read_b128 v[188:191], v182 offset:33792
	ds_read_b128 v[192:195], v182 offset:34816
	ds_read_b128 v[196:199], v182 offset:35840
	ds_read_b128 v[220:223], v182 offset:36864
	ds_read_b128 v[224:227], v182 offset:37888
	ds_read_b128 v[228:231], v182 offset:38912
	ds_read_b128 v[232:235], v182 offset:39936
	global_load_lds_dwordx4 v162, s[28:29]
	s_mov_b32 m0, s31
	s_nop 0
	global_load_lds_dwordx4 v166, s[28:29]
	s_waitcnt vmcnt(8)
	s_waitcnt lgkmcnt(0)
	s_barrier
	s_setprio 1
	s_waitcnt lgkmcnt(0)
	v_mfma_f32_16x16x128_f8f6f4 v[158:161], v[2:9], v[184:191], v[158:161]
	v_mfma_f32_16x16x128_f8f6f4 v[154:157], v[10:17], v[184:191], v[154:157]
	v_mfma_f32_16x16x128_f8f6f4 v[142:145], v[2:9], v[192:199], v[142:145]
	v_mfma_f32_16x16x128_f8f6f4 v[138:141], v[10:17], v[192:199], v[138:141]
	v_mfma_f32_16x16x128_f8f6f4 v[126:129], v[2:9], v[220:227], v[126:129]
	v_mfma_f32_16x16x128_f8f6f4 v[122:125], v[10:17], v[220:227], v[122:125]
	v_mfma_f32_16x16x128_f8f6f4 v[110:113], v[2:9], v[228:235], v[110:113]
	v_mfma_f32_16x16x128_f8f6f4 v[106:109], v[10:17], v[228:235], v[106:109]
	s_setprio 0
	s_setprio 1
	v_mfma_f32_16x16x128_f8f6f4 v[150:153], v[18:25], v[184:191], v[150:153]
	v_mfma_f32_16x16x128_f8f6f4 v[146:149], v[26:33], v[184:191], v[146:149]
	v_mfma_f32_16x16x128_f8f6f4 v[134:137], v[18:25], v[192:199], v[134:137]
	v_mfma_f32_16x16x128_f8f6f4 v[130:133], v[26:33], v[192:199], v[130:133]
	v_mfma_f32_16x16x128_f8f6f4 v[118:121], v[18:25], v[220:227], v[118:121]
	v_mfma_f32_16x16x128_f8f6f4 v[114:117], v[26:33], v[220:227], v[114:117]
	v_mfma_f32_16x16x128_f8f6f4 v[102:105], v[18:25], v[228:235], v[102:105]
	v_mfma_f32_16x16x128_f8f6f4 v[98:101], v[26:33], v[228:235], v[98:101]
	s_setprio 0
	s_barrier
	s_add_u32 s28, s26, 0x80000
	s_addc_u32 s29, s27, 0
	s_add_i32 s45, s45, s0
	s_mov_b32 m0, s45
	ds_read_b128 v[184:187], v182 offset:49152
	ds_read_b128 v[188:191], v182 offset:50176
	ds_read_b128 v[192:195], v182 offset:51200
	ds_read_b128 v[196:199], v182 offset:52224
	ds_read_b128 v[220:223], v182 offset:53248
	ds_read_b128 v[224:227], v182 offset:54272
	ds_read_b128 v[228:231], v182 offset:55296
	ds_read_b128 v[232:235], v182 offset:56320
	global_load_lds_dwordx4 v164, s[28:29]
	s_add_i32 m0, s45, 0x2000
	s_add_u32 s26, s26, 0x84000
	s_addc_u32 s27, s27, 0
	global_load_lds_dwordx4 v168, s[28:29]
	s_add_i32 s28, s46, s0
	s_mov_b32 m0, s28
	s_nop 0
	global_load_lds_dwordx4 v164, s[26:27]
	s_add_i32 m0, s28, 0x2000
	s_nop 0
	global_load_lds_dwordx4 v168, s[26:27]
	s_mov_b32 m0, s36
	s_nop 0
	global_load_lds_dwordx4 v162, s[24:25]
	s_mov_b32 m0, s37
	s_nop 0
	global_load_lds_dwordx4 v166, s[24:25]
	s_waitcnt vmcnt(8)
	s_waitcnt lgkmcnt(0)
	s_barrier
	s_setprio 1
	s_waitcnt lgkmcnt(0)
	v_mfma_f32_16x16x128_f8f6f4 v[94:97], v[2:9], v[184:191], v[94:97]
	v_mfma_f32_16x16x128_f8f6f4 v[90:93], v[10:17], v[184:191], v[90:93]
	v_mfma_f32_16x16x128_f8f6f4 v[78:81], v[2:9], v[192:199], v[78:81]
	v_mfma_f32_16x16x128_f8f6f4 v[74:77], v[10:17], v[192:199], v[74:77]
	v_mfma_f32_16x16x128_f8f6f4 v[62:65], v[2:9], v[220:227], v[62:65]
	v_mfma_f32_16x16x128_f8f6f4 v[58:61], v[10:17], v[220:227], v[58:61]
	v_mfma_f32_16x16x128_f8f6f4 v[46:49], v[2:9], v[228:235], v[46:49]
	v_mfma_f32_16x16x128_f8f6f4 v[42:45], v[10:17], v[228:235], v[42:45]
	s_setprio 0
	s_setprio 1
	v_mfma_f32_16x16x128_f8f6f4 v[86:89], v[18:25], v[184:191], v[86:89]
	v_mfma_f32_16x16x128_f8f6f4 v[82:85], v[26:33], v[184:191], v[82:85]
	v_mfma_f32_16x16x128_f8f6f4 v[70:73], v[18:25], v[192:199], v[70:73]
	v_mfma_f32_16x16x128_f8f6f4 v[66:69], v[26:33], v[192:199], v[66:69]
	v_mfma_f32_16x16x128_f8f6f4 v[54:57], v[18:25], v[220:227], v[54:57]
	v_mfma_f32_16x16x128_f8f6f4 v[50:53], v[26:33], v[220:227], v[50:53]
	v_mfma_f32_16x16x128_f8f6f4 v[38:41], v[18:25], v[228:235], v[38:41]
	v_mfma_f32_16x16x128_f8f6f4 v[34:37], v[26:33], v[228:235], v[34:37]
	s_setprio 0
	s_barrier
	s_add_i32 s44, s44, 2
	s_add_u32 s42, s42, 0x100000
	s_addc_u32 s43, s43, 0
	s_add_u32 s22, s22, 0x200000
	s_addc_u32 s23, s23, 0
	s_cmpk_gt_u32 s44, 0x6d
	s_cbranch_scc0 .LBB0_2714
	s_and_b64 vcc, exec, s[10:11]
	s_cbranch_vccz .LBB0_2717
	s_barrier
